# prologue cpart loop (WGs 0-31): 4 trips of 40 loads with counted waits instead of 16 serial trips
# baseline (speedup 1.0000x reference)
.LBB0_20:
	s_or_b64 exec, exec, s[8:9]
	s_cmp_lt_i32 s2, 32
	s_cbranch_scc0 .LBB0_24
	s_lshl_b32 s3, s2, 1
	v_ashrrev_i32_e32 v3, 8, v2
	v_add_u32_e32 v1, s3, v3
	v_mov_b32_e32 v4, 0x58
	v_cmp_gt_u32_e32 vcc, 32, v1
	v_mov_b32_e32 v5, 0
	v_mov_b32_e32 v8, 0x60
	v_cndmask_b32_e64 v4, v4, 64, vcc
	v_lshl_add_u64 v[6:7], s[0:1], 0, v[4:5]
	global_load_dwordx2 v[6:7], v[6:7], off
	v_and_b32_e32 v4, 31, v1
	v_mov_b32_e32 v9, 0x48
	v_lshlrev_b32_e32 v4, 9, v4
	s_mov_b64 s[4:5], 0x1c00
	s_mov_b64 s[6:7], 0
	s_mov_b64 s[8:9], 0x2000
	s_waitcnt vmcnt(0)
	v_lshl_add_u64 v[6:7], v[6:7], 0, v[4:5]
	v_cndmask_b32_e32 v4, v8, v9, vcc
	v_lshl_add_u64 v[8:9], s[0:1], 0, v[4:5]
	global_load_dwordx2 v[12:13], v[8:9], off
	v_and_b32_e32 v8, 0xff, v2
	v_add_u16_e32 v2, s3, v3
	v_lshlrev_b32_e32 v3, 2, v8
	v_and_b32_e32 v2, 31, v2
	v_lshl_or_b32 v4, v2, 17, v3
	s_waitcnt vmcnt(0)
	v_lshl_add_u64 v[2:3], v[12:13], 0, v[4:5]
	v_lshl_add_u64 v[2:3], v[2:3], 0, s[4:5]
	s_mov_b32 s40, 0x2000
	s_mov_b32 s41, 0
	s_mov_b32 s42, 0x4000
	s_mov_b32 s43, 0
	s_mov_b32 s44, 0x6000
	s_mov_b32 s45, 0
	s_mov_b32 s46, 0xfffff000
	s_mov_b32 s47, -1
	s_mov_b32 s48, 0x8000
	s_mov_b32 s49, 0
.LBB0_22:
	v_lshl_add_u64 v[50:51], v[6:7], 0, s[6:7]
	s_waitcnt lgkmcnt(0)
	global_load_dwordx4 v[52:55], v[50:51], off
	global_load_dwordx4 v[56:59], v[50:51], off offset:16
	global_load_dwordx4 v[60:63], v[50:51], off offset:32
	global_load_dwordx4 v[64:67], v[50:51], off offset:48
	global_load_dwordx4 v[68:71], v[50:51], off offset:64
	global_load_dwordx4 v[72:75], v[50:51], off offset:80
	global_load_dwordx4 v[76:79], v[50:51], off offset:96
	global_load_dwordx4 v[80:83], v[50:51], off offset:112
	v_lshl_add_u64 v[84:85], v[2:3], 0, s[40:41]
	v_lshl_add_u64 v[86:87], v[2:3], 0, s[42:43]
	v_lshl_add_u64 v[88:89], v[2:3], 0, s[44:45]
	v_lshl_add_u64 v[90:91], v[2:3], 0, s[46:47]
	v_lshl_add_u64 v[92:93], v[84:85], 0, s[46:47]
	v_lshl_add_u64 v[94:95], v[86:87], 0, s[46:47]
	v_lshl_add_u64 v[96:97], v[88:89], 0, s[46:47]
	global_load_dword v98, v[90:91], off offset:-3072
	global_load_dword v99, v[90:91], off offset:-2048
	global_load_dword v100, v[90:91], off offset:-1024
	global_load_dword v101, v[2:3], off offset:-4096
	global_load_dword v102, v[2:3], off offset:-3072
	global_load_dword v103, v[2:3], off offset:-2048
	global_load_dword v104, v[2:3], off offset:-1024
	global_load_dword v105, v[2:3], off
	global_load_dword v106, v[92:93], off offset:-3072
	global_load_dword v107, v[92:93], off offset:-2048
	global_load_dword v108, v[92:93], off offset:-1024
	global_load_dword v109, v[84:85], off offset:-4096
	global_load_dword v110, v[84:85], off offset:-3072
	global_load_dword v111, v[84:85], off offset:-2048
	global_load_dword v112, v[84:85], off offset:-1024
	global_load_dword v113, v[84:85], off
	global_load_dword v114, v[94:95], off offset:-3072
	global_load_dword v115, v[94:95], off offset:-2048
	global_load_dword v116, v[94:95], off offset:-1024
	global_load_dword v117, v[86:87], off offset:-4096
	global_load_dword v118, v[86:87], off offset:-3072
	global_load_dword v119, v[86:87], off offset:-2048
	global_load_dword v120, v[86:87], off offset:-1024
	global_load_dword v121, v[86:87], off
	global_load_dword v122, v[96:97], off offset:-3072
	global_load_dword v123, v[96:97], off offset:-2048
	global_load_dword v124, v[96:97], off offset:-1024
	global_load_dword v125, v[88:89], off offset:-4096
	global_load_dword v126, v[88:89], off offset:-3072
	global_load_dword v127, v[88:89], off offset:-2048
	global_load_dword v128, v[88:89], off offset:-1024
	global_load_dword v129, v[88:89], off
	s_add_u32 s6, s6, 0x80
	s_addc_u32 s7, s7, 0
	s_nop 0
	v_lshl_add_u64 v[2:3], v[2:3], 0, s[48:49]
	s_cmpk_eq_i32 s6, 0x200
	s_waitcnt vmcnt(31)
	v_fmac_f32_e32 v5, v52, v98
	s_waitcnt vmcnt(30)
	v_fmac_f32_e32 v5, v53, v99
	s_waitcnt vmcnt(29)
	v_fmac_f32_e32 v5, v54, v100
	s_waitcnt vmcnt(28)
	v_fmac_f32_e32 v5, v55, v101
	s_waitcnt vmcnt(27)
	v_fmac_f32_e32 v5, v56, v102
	s_waitcnt vmcnt(26)
	v_fmac_f32_e32 v5, v57, v103
	s_waitcnt vmcnt(25)
	v_fmac_f32_e32 v5, v58, v104
	s_waitcnt vmcnt(24)
	v_fmac_f32_e32 v5, v59, v105
	s_waitcnt vmcnt(23)
	v_fmac_f32_e32 v5, v60, v106
	s_waitcnt vmcnt(22)
	v_fmac_f32_e32 v5, v61, v107
	s_waitcnt vmcnt(21)
	v_fmac_f32_e32 v5, v62, v108
	s_waitcnt vmcnt(20)
	v_fmac_f32_e32 v5, v63, v109
	s_waitcnt vmcnt(19)
	v_fmac_f32_e32 v5, v64, v110
	s_waitcnt vmcnt(18)
	v_fmac_f32_e32 v5, v65, v111
	s_waitcnt vmcnt(17)
	v_fmac_f32_e32 v5, v66, v112
	s_waitcnt vmcnt(16)
	v_fmac_f32_e32 v5, v67, v113
	s_waitcnt vmcnt(15)
	v_fmac_f32_e32 v5, v68, v114
	s_waitcnt vmcnt(14)
	v_fmac_f32_e32 v5, v69, v115
	s_waitcnt vmcnt(13)
	v_fmac_f32_e32 v5, v70, v116
	s_waitcnt vmcnt(12)
	v_fmac_f32_e32 v5, v71, v117
	s_waitcnt vmcnt(11)
	v_fmac_f32_e32 v5, v72, v118
	s_waitcnt vmcnt(10)
	v_fmac_f32_e32 v5, v73, v119
	s_waitcnt vmcnt(9)
	v_fmac_f32_e32 v5, v74, v120
	s_waitcnt vmcnt(8)
	v_fmac_f32_e32 v5, v75, v121
	s_waitcnt vmcnt(7)
	v_fmac_f32_e32 v5, v76, v122
	s_waitcnt vmcnt(6)
	v_fmac_f32_e32 v5, v77, v123
	s_waitcnt vmcnt(5)
	v_fmac_f32_e32 v5, v78, v124
	s_waitcnt vmcnt(4)
	v_fmac_f32_e32 v5, v79, v125
	s_waitcnt vmcnt(3)
	v_fmac_f32_e32 v5, v80, v126
	s_waitcnt vmcnt(2)
	v_fmac_f32_e32 v5, v81, v127
	s_waitcnt vmcnt(1)
	v_fmac_f32_e32 v5, v82, v128
	s_waitcnt vmcnt(0)
	v_fmac_f32_e32 v5, v83, v129
	s_cbranch_scc0 .LBB0_22
	v_lshl_or_b32 v2, v1, 8, v8
	v_ashrrev_i32_e32 v3, 31, v2
	v_lshl_add_u64 v[2:3], v[2:3], 2, v[10:11]
	v_add_co_u32_e32 v2, vcc, 0x243f0000, v2
	s_nop 1
	v_addc_co_u32_e32 v3, vcc, 0, v3, vcc
	global_store_dword v[2:3], v5, off
